# c5_mla_diff_fastpaths
# baseline (speedup 1.0000x reference)
.LBB0_871:
	s_add_i32 s80, s75, -3
	s_lshl_b32 s76, s74, 14
	s_add_i32 s8, s69, s76
	v_lshl_add_u64 v[2:3], v[226:227], 0, s[34:35]
	s_mov_b32 m0, s8
	s_nop 0
	global_load_lds_dwordx4 v[2:3], off
	s_add_i32 m0, s8, 0x2000
	s_mul_i32 s8, s60, 0x6300
	s_add_i32 s61, s68, s8
	global_load_lds_dwordx4 v[226:227], off
	s_add_i32 m0, s61, 0xc000
	s_add_i32 s8, s75, -1
	s_cmp_lt_u32 s8, s77
	s_cselect_b32 s8, s8, s73
	s_lshl_b32 s8, s8, 6
	s_lshl_b64 s[58:59], s[8:9], 12
	v_lshl_add_u64 v[2:3], v[218:219], 0, s[58:59]
	global_load_lds_dwordx4 v[2:3], off
	v_lshl_add_u64 v[2:3], v[2:3], 0, s[12:13]
	s_add_i32 m0, s61, 0xe100
	s_lshl_b64 s[82:83], s[8:9], 7
	global_load_lds_dwordx4 v[2:3], off
	v_lshl_add_u64 v[2:3], v[224:225], 0, s[82:83]
	s_add_i32 m0, s61, 0x10200
	s_nop 0
	global_load_lds_dwordx4 v[2:3], off
	s_mul_i32 s8, s79, 0x6300
	s_add_i32 s8, s8, 0
	v_add_u32_e32 v0, s8, v237
	ds_read_b128 v[2:5], v0 offset:49152
	ds_read_b128 v[6:9], v0 offset:50176
	s_waitcnt lgkmcnt(0)
	v_mfma_f32_32x32x16_bf16 v[112:127], v[2:5], v[188:191], 0
	v_mfma_f32_32x32x16_bf16 v[128:143], v[6:9], v[188:191], 0
	ds_read_b128 v[2:5], v0 offset:51264
	ds_read_b128 v[6:9], v0 offset:52288
	s_waitcnt lgkmcnt(0)
	v_mfma_f32_32x32x16_bf16 v[112:127], v[2:5], v[184:187], v[112:127]
	v_mfma_f32_32x32x16_bf16 v[128:143], v[6:9], v[184:187], v[128:143]
	ds_read_b128 v[2:5], v0 offset:53376
	ds_read_b128 v[6:9], v0 offset:54400
	s_waitcnt lgkmcnt(0)
	v_mfma_f32_32x32x16_bf16 v[112:127], v[2:5], v[180:183], v[112:127]
	v_mfma_f32_32x32x16_bf16 v[128:143], v[6:9], v[180:183], v[128:143]
	ds_read_b128 v[2:5], v0 offset:55488
	ds_read_b128 v[6:9], v0 offset:56512
	s_waitcnt lgkmcnt(0)
	v_mfma_f32_32x32x16_bf16 v[112:127], v[2:5], v[176:179], v[112:127]
	v_mfma_f32_32x32x16_bf16 v[128:143], v[6:9], v[176:179], v[128:143]
	ds_read_b128 v[2:5], v0 offset:57600
	ds_read_b128 v[6:9], v0 offset:58624
	s_waitcnt lgkmcnt(0)
	v_mfma_f32_32x32x16_bf16 v[112:127], v[2:5], v[172:175], v[112:127]
	v_mfma_f32_32x32x16_bf16 v[128:143], v[6:9], v[172:175], v[128:143]
	ds_read_b128 v[2:5], v0 offset:59712
	ds_read_b128 v[6:9], v0 offset:60736
	s_waitcnt lgkmcnt(0)
	v_mfma_f32_32x32x16_bf16 v[112:127], v[2:5], v[168:171], v[112:127]
	v_mfma_f32_32x32x16_bf16 v[128:143], v[6:9], v[168:171], v[128:143]
	ds_read_b128 v[2:5], v0 offset:61824
	ds_read_b128 v[6:9], v0 offset:62848
	s_waitcnt lgkmcnt(0)
	v_mfma_f32_32x32x16_bf16 v[112:127], v[2:5], v[164:167], v[112:127]
	v_mfma_f32_32x32x16_bf16 v[128:143], v[6:9], v[164:167], v[128:143]
	ds_read_b128 v[2:5], v0 offset:63936
	ds_read_b128 v[6:9], v0 offset:64960
	v_add_u32_e32 v0, 0xc000, v0
	s_waitcnt lgkmcnt(0)
	v_mfma_f32_32x32x16_bf16 v[112:127], v[2:5], v[160:163], v[112:127]
	ds_read_b128 v[2:5], v0 offset:17920
	ds_read_b128 v[10:13], v0 offset:16896
	v_mfma_f32_32x32x16_bf16 v[128:143], v[6:9], v[160:163], v[128:143]
	ds_read_b128 v[6:9], v0 offset:20032
	ds_read_b128 v[192:195], v0 offset:19008
	ds_read_b128 v[196:199], v0 offset:22144
	ds_read_b128 v[200:203], v0 offset:21120
	ds_read_b128 v[204:207], v0 offset:24256
	ds_read_b128 v[208:211], v0 offset:23232
	v_add_f32_e32 v0, 0, v96
	v_add_f32_e32 v0, v97, v0
	v_add_f32_e32 v0, v98, v0
	v_add_f32_e32 v0, v99, v0
	v_add_f32_e32 v0, v100, v0
	v_add_f32_e32 v0, v101, v0
	s_waitcnt lgkmcnt(0)
	v_mfma_f32_32x32x16_bf16 v[112:127], v[10:13], v[156:159], v[112:127]
	v_add_f32_e32 v0, v102, v0
	v_add_f32_e32 v0, v103, v0
	v_add_f32_e32 v0, v104, v0
	v_add_f32_e32 v0, v105, v0
	v_add_f32_e32 v0, v106, v0
	v_add_f32_e32 v0, v107, v0
	v_add_f32_e32 v0, v108, v0
	v_mfma_f32_32x32x16_bf16 v[128:143], v[2:5], v[156:159], v[128:143]
	v_add_f32_e32 v0, v109, v0
	v_add_f32_e32 v0, v110, v0
	v_add_f32_e32 v0, v111, v0
	v_add_f32_e32 v0, v80, v0
	v_add_f32_e32 v0, v81, v0
	v_add_f32_e32 v0, v82, v0
	v_add_f32_e32 v0, v83, v0
	v_mfma_f32_32x32x16_bf16 v[112:127], v[192:195], v[152:155], v[112:127]
	v_add_f32_e32 v0, v84, v0
	v_add_f32_e32 v0, v85, v0
	v_add_f32_e32 v0, v86, v0
	v_add_f32_e32 v0, v87, v0
	v_add_f32_e32 v0, v88, v0
	v_add_f32_e32 v0, v89, v0
	v_add_f32_e32 v0, v90, v0
	v_mfma_f32_32x32x16_bf16 v[128:143], v[6:9], v[152:155], v[128:143]
	v_add_f32_e32 v0, v91, v0
	v_add_f32_e32 v0, v92, v0
	v_add_f32_e32 v0, v93, v0
	v_add_f32_e32 v0, v94, v0
	v_add_f32_e32 v14, v95, v0
	v_mov_b32_e32 v15, v14
	s_nop 1
	v_permlane32_swap_b32_e32 v14, v15
	v_mfma_f32_32x32x16_bf16 v[112:127], v[200:203], v[148:151], v[112:127]
	v_cvt_pk_bf16_f32 v192, v96, v97
	v_cvt_pk_bf16_f32 v193, v98, v99
	v_cvt_pk_bf16_f32 v194, v100, v101
	v_cvt_pk_bf16_f32 v195, v102, v103
	v_cvt_pk_bf16_f32 v10, v104, v105
	v_cvt_pk_bf16_f32 v11, v106, v107
	v_cvt_pk_bf16_f32 v12, v108, v109
	v_mfma_f32_32x32x16_bf16 v[128:143], v[196:199], v[148:151], v[128:143]
	v_cvt_pk_bf16_f32 v13, v110, v111
	v_cvt_pk_bf16_f32 v6, v80, v81
	v_cvt_pk_bf16_f32 v7, v82, v83
	v_cvt_pk_bf16_f32 v8, v84, v85
	v_cvt_pk_bf16_f32 v9, v86, v87
	v_cvt_pk_bf16_f32 v2, v88, v89
	v_cvt_pk_bf16_f32 v3, v90, v91
	v_mfma_f32_32x32x16_bf16 v[112:127], v[208:211], v[144:147], v[112:127]
	v_cvt_pk_bf16_f32 v4, v92, v93
	v_cvt_pk_bf16_f32 v5, v94, v95
	v_mfma_f32_32x32x16_bf16 v[128:143], v[204:207], v[144:147], v[128:143]
	s_cmp_gt_i32 s80, s72
	s_cbranch_scc0 .Lfm_odd
	s_cselect_b64 vcc, -1, 0
	s_nop 8
	v_cndmask_b32_e32 v97, v113, v231, vcc
	v_cndmask_b32_e32 v96, v112, v231, vcc
	v_max_f32_e32 v112, v97, v97
	v_max_f32_e32 v113, v96, v96
	v_cndmask_b32_e32 v99, v115, v231, vcc
	v_cndmask_b32_e32 v98, v114, v231, vcc
	v_max_f32_e32 v112, v113, v112
	v_cndmask_b32_e32 v101, v117, v231, vcc
	v_cndmask_b32_e32 v100, v116, v231, vcc
	v_max3_f32 v112, v112, v98, v99
	v_cndmask_b32_e32 v103, v119, v231, vcc
	v_cndmask_b32_e32 v102, v118, v231, vcc
	v_max3_f32 v112, v112, v100, v101
	v_cndmask_b32_e32 v105, v121, v231, vcc
	v_cndmask_b32_e32 v104, v120, v231, vcc
	v_max3_f32 v112, v112, v102, v103
	v_cndmask_b32_e32 v107, v123, v231, vcc
	v_cndmask_b32_e32 v106, v122, v231, vcc
	v_max3_f32 v112, v112, v104, v105
	v_cndmask_b32_e32 v109, v125, v231, vcc
	v_cndmask_b32_e32 v108, v124, v231, vcc
	v_max3_f32 v112, v112, v106, v107
	v_cndmask_b32_e32 v111, v127, v231, vcc
	v_cndmask_b32_e32 v110, v126, v231, vcc
	v_max3_f32 v112, v112, v108, v109
	v_cndmask_b32_e32 v81, v129, v231, vcc
	v_cndmask_b32_e32 v80, v128, v231, vcc
	v_max3_f32 v112, v112, v110, v111
	v_cndmask_b32_e32 v83, v131, v231, vcc
	v_cndmask_b32_e32 v82, v130, v231, vcc
	v_max3_f32 v112, v112, v80, v81
	v_cndmask_b32_e32 v85, v133, v231, vcc
	v_cndmask_b32_e32 v84, v132, v231, vcc
	v_max3_f32 v112, v112, v82, v83
	v_cndmask_b32_e32 v87, v135, v231, vcc
	v_cndmask_b32_e32 v86, v134, v231, vcc
	v_max3_f32 v112, v112, v84, v85
	v_cndmask_b32_e32 v89, v137, v231, vcc
	v_cndmask_b32_e32 v88, v136, v231, vcc
	v_max3_f32 v112, v112, v86, v87
	v_cndmask_b32_e32 v91, v139, v231, vcc
	v_cndmask_b32_e32 v90, v138, v231, vcc
	v_max3_f32 v112, v112, v88, v89
	v_lshl_add_u32 v0, s60, 14, v235
	ds_read_b64_tr_b16 v[208:209], v0 offset:0
	v_cndmask_b32_e32 v93, v141, v231, vcc
	v_cndmask_b32_e32 v92, v140, v231, vcc
	v_max3_f32 v112, v112, v90, v91
	ds_read_b64_tr_b16 v[210:211], v0 offset:0x800
	v_cndmask_b32_e32 v95, v143, v231, vcc
	v_cndmask_b32_e32 v94, v142, v231, vcc
	v_max3_f32 v112, v112, v92, v93
	ds_read_b64_tr_b16 v[204:205], v0 offset:0x1000
	v_max3_f32 v112, v112, v94, v95
	ds_read_b64_tr_b16 v[206:207], v0 offset:0x1800
	v_mov_b32_e32 v113, v112
	ds_read_b64_tr_b16 v[200:201], v0 offset:0x2000
	s_nop 1
	v_permlane32_swap_b32_e32 v112, v113
	ds_read_b64_tr_b16 v[202:203], v0 offset:0x2800
	v_max_f32_e32 v113, v113, v113
	v_max_f32_e32 v112, v112, v112
	ds_read_b64_tr_b16 v[196:197], v0 offset:0x3000
	v_max_f32_e32 v112, v112, v113
	ds_read_b64_tr_b16 v[198:199], v0 offset:0x3800
	v_sub_f32_e32 v113, v112, v236
	v_cmp_ge_f32_e32 vcc, s29, v113
	s_cmp_eq_u64 vcc, exec
	v_mov_b32_e32 v240, 1.0
	s_cbranch_scc0 .LBB0_883

.Lresc_mla_odd:
	v_cmp_gt_f32_e32 vcc, 1.0, v240
	s_cbranch_vccz .LBB0_876
	s_and_saveexec_b64 s[60:61], s[4:5]
	ds_write_b32 v233, v240 offset:128
	s_or_b64 exec, exec, s[60:61]
	s_waitcnt lgkmcnt(0)
	ds_read_b128 v[2:5], v232 offset:224
	ds_read_b128 v[6:9], v232 offset:192
	ds_read_b128 v[10:13], v232 offset:160
	ds_read_b128 v[112:115], v232 offset:128
	s_waitcnt lgkmcnt(0)
	v_pk_mul_f32 v[78:79], v[78:79], v[4:5]
	v_pk_mul_f32 v[74:75], v[74:75], v[8:9]
	v_pk_mul_f32 v[70:71], v[70:71], v[12:13]
	v_pk_mul_f32 v[66:67], v[66:67], v[114:115]
	v_pk_mul_f32 v[76:77], v[76:77], v[2:3]
	v_pk_mul_f32 v[72:73], v[72:73], v[6:7]
	v_pk_mul_f32 v[68:69], v[68:69], v[10:11]
	v_pk_mul_f32 v[64:65], v[64:65], v[112:113]
	v_pk_mul_f32 v[62:63], v[62:63], v[4:5]
	v_pk_mul_f32 v[58:59], v[58:59], v[8:9]
	v_pk_mul_f32 v[54:55], v[54:55], v[12:13]
	v_pk_mul_f32 v[50:51], v[50:51], v[114:115]
	v_pk_mul_f32 v[60:61], v[60:61], v[2:3]
	v_pk_mul_f32 v[56:57], v[56:57], v[6:7]
	v_pk_mul_f32 v[52:53], v[52:53], v[10:11]
	v_pk_mul_f32 v[48:49], v[48:49], v[112:113]
	v_pk_mul_f32 v[46:47], v[46:47], v[4:5]
	v_pk_mul_f32 v[42:43], v[42:43], v[8:9]
	v_pk_mul_f32 v[38:39], v[38:39], v[12:13]
	v_pk_mul_f32 v[34:35], v[34:35], v[114:115]
	v_pk_mul_f32 v[44:45], v[44:45], v[2:3]
	v_pk_mul_f32 v[40:41], v[40:41], v[6:7]
	v_pk_mul_f32 v[36:37], v[36:37], v[10:11]
	v_pk_mul_f32 v[32:33], v[32:33], v[112:113]
	v_pk_mul_f32 v[30:31], v[30:31], v[4:5]
	v_pk_mul_f32 v[26:27], v[26:27], v[8:9]
	v_pk_mul_f32 v[22:23], v[22:23], v[12:13]
	v_pk_mul_f32 v[18:19], v[18:19], v[114:115]
	v_pk_mul_f32 v[28:29], v[28:29], v[2:3]
	v_pk_mul_f32 v[24:25], v[24:25], v[6:7]
	v_pk_mul_f32 v[20:21], v[20:21], v[10:11]
	v_pk_mul_f32 v[16:17], v[16:17], v[112:113]
.LBB0_876:
	s_waitcnt vmcnt(0)
	s_add_i32 s60, s74, 1
	s_cmp_lg_u32 s74, 2
	s_cselect_b32 s81, s60, 0
	s_waitcnt vmcnt(0)
	s_barrier
	s_lshl_b32 s78, s81, 14
	s_add_i32 s60, s69, s78
	v_lshl_add_u64 v[2:3], v[222:223], 0, s[58:59]
	v_lshl_add_u64 v[4:5], v[2:3], 0, s[14:15]
	s_mov_b32 m0, s60
	s_add_i32 s8, s8, s70
	global_load_lds_dwordx4 v[4:5], off
	v_lshl_add_u64 v[2:3], v[2:3], 0, s[16:17]
	s_add_i32 m0, s60, 0x2000
	s_add_i32 s82, s8, s71
	global_load_lds_dwordx4 v[2:3], off
	s_add_i32 m0, s82, 0xc000
	s_cmp_ge_u32 s75, s77
	s_cselect_b64 s[58:59], -1, 0
	s_cmp_lt_u32 s75, s77
	s_cselect_b32 s8, s75, s73
	s_lshl_b32 s8, s8, 6
	s_lshl_b64 s[60:61], s[8:9], 12
	v_lshl_add_u64 v[2:3], v[218:219], 0, s[60:61]
	global_load_lds_dwordx4 v[2:3], off
	v_lshl_add_u64 v[2:3], v[2:3], 0, s[12:13]
	s_add_i32 m0, s82, 0xe100
	s_lshl_b64 s[60:61], s[8:9], 7
	global_load_lds_dwordx4 v[2:3], off
	v_lshl_add_u64 v[2:3], v[224:225], 0, s[60:61]
	s_add_i32 m0, s82, 0x10200
	s_nop 0
	global_load_lds_dwordx4 v[2:3], off
	s_mul_i32 s8, s74, 0x6300
	v_add_u32_e32 v0, s8, v238
	ds_read_b128 v[2:5], v0 offset:49152
	ds_read_b128 v[6:9], v0 offset:50176
	s_waitcnt lgkmcnt(0)
	v_mfma_f32_32x32x16_bf16 v[112:127], v[2:5], v[188:191], 0
	v_mfma_f32_32x32x16_bf16 v[128:143], v[6:9], v[188:191], 0
	ds_read_b128 v[2:5], v0 offset:51264
	ds_read_b128 v[6:9], v0 offset:52288
	s_waitcnt lgkmcnt(0)
	v_mfma_f32_32x32x16_bf16 v[112:127], v[2:5], v[184:187], v[112:127]
	v_mfma_f32_32x32x16_bf16 v[128:143], v[6:9], v[184:187], v[128:143]
	ds_read_b128 v[2:5], v0 offset:53376
	ds_read_b128 v[6:9], v0 offset:54400
	s_waitcnt lgkmcnt(0)
	v_mfma_f32_32x32x16_bf16 v[112:127], v[2:5], v[180:183], v[112:127]
	v_mfma_f32_32x32x16_bf16 v[128:143], v[6:9], v[180:183], v[128:143]
	ds_read_b128 v[2:5], v0 offset:55488
	ds_read_b128 v[6:9], v0 offset:56512
	s_waitcnt lgkmcnt(0)
	v_mfma_f32_32x32x16_bf16 v[112:127], v[2:5], v[176:179], v[112:127]
	v_mfma_f32_32x32x16_bf16 v[128:143], v[6:9], v[176:179], v[128:143]
	ds_read_b128 v[2:5], v0 offset:57600
	ds_read_b128 v[6:9], v0 offset:58624
	s_waitcnt lgkmcnt(0)
	v_mfma_f32_32x32x16_bf16 v[112:127], v[2:5], v[172:175], v[112:127]
	v_mfma_f32_32x32x16_bf16 v[128:143], v[6:9], v[172:175], v[128:143]
	ds_read_b128 v[2:5], v0 offset:59712
	ds_read_b128 v[6:9], v0 offset:60736
	s_waitcnt lgkmcnt(0)
	v_mfma_f32_32x32x16_bf16 v[112:127], v[2:5], v[168:171], v[112:127]
	v_mfma_f32_32x32x16_bf16 v[128:143], v[6:9], v[168:171], v[128:143]
	ds_read_b128 v[2:5], v0 offset:61824
	ds_read_b128 v[6:9], v0 offset:62848
	s_waitcnt lgkmcnt(0)
	v_mfma_f32_32x32x16_bf16 v[112:127], v[2:5], v[164:167], v[112:127]
	v_mfma_f32_32x32x16_bf16 v[128:143], v[6:9], v[164:167], v[128:143]
	ds_read_b128 v[2:5], v0 offset:63936
	ds_read_b128 v[6:9], v0 offset:64960
	v_add_u32_e32 v0, 0xc000, v0
	s_waitcnt lgkmcnt(0)
	v_mfma_f32_32x32x16_bf16 v[112:127], v[2:5], v[160:163], v[112:127]
	ds_read_b128 v[2:5], v0 offset:17920
	ds_read_b128 v[10:13], v0 offset:16896
	v_mfma_f32_32x32x16_bf16 v[128:143], v[6:9], v[160:163], v[128:143]
	ds_read_b128 v[6:9], v0 offset:20032
	ds_read_b128 v[192:195], v0 offset:19008
	ds_read_b128 v[196:199], v0 offset:22144
	ds_read_b128 v[200:203], v0 offset:21120
	ds_read_b128 v[204:207], v0 offset:24256
	ds_read_b128 v[208:211], v0 offset:23232
	v_add_f32_e32 v0, 0, v96
	v_add_f32_e32 v0, v97, v0
	v_add_f32_e32 v0, v98, v0
	v_add_f32_e32 v0, v99, v0
	v_add_f32_e32 v0, v100, v0
	v_add_f32_e32 v0, v101, v0
	s_waitcnt lgkmcnt(0)
	v_mfma_f32_32x32x16_bf16 v[112:127], v[10:13], v[156:159], v[112:127]
	v_add_f32_e32 v0, v102, v0
	v_add_f32_e32 v0, v103, v0
	v_add_f32_e32 v0, v104, v0
	v_add_f32_e32 v0, v105, v0
	v_add_f32_e32 v0, v106, v0
	v_add_f32_e32 v0, v107, v0
	v_add_f32_e32 v0, v108, v0
	v_mfma_f32_32x32x16_bf16 v[128:143], v[2:5], v[156:159], v[128:143]
	v_add_f32_e32 v0, v109, v0
	v_add_f32_e32 v0, v110, v0
	v_add_f32_e32 v0, v111, v0
	v_add_f32_e32 v0, v80, v0
	v_add_f32_e32 v0, v81, v0
	v_add_f32_e32 v0, v82, v0
	v_add_f32_e32 v0, v83, v0
	v_mfma_f32_32x32x16_bf16 v[112:127], v[192:195], v[152:155], v[112:127]
	v_add_f32_e32 v0, v84, v0
	v_add_f32_e32 v0, v85, v0
	v_add_f32_e32 v0, v86, v0
	v_add_f32_e32 v0, v87, v0
	v_add_f32_e32 v0, v88, v0
	v_add_f32_e32 v0, v89, v0
	v_add_f32_e32 v0, v90, v0
	v_mfma_f32_32x32x16_bf16 v[128:143], v[6:9], v[152:155], v[128:143]
	v_add_f32_e32 v0, v91, v0
	v_add_f32_e32 v0, v92, v0
	v_add_f32_e32 v0, v93, v0
	v_add_f32_e32 v0, v94, v0
	v_add_f32_e32 v241, v95, v0
	v_mov_b32_e32 v242, v241
	s_nop 1
	v_permlane32_swap_b32_e32 v241, v242
	v_mfma_f32_32x32x16_bf16 v[112:127], v[200:203], v[148:151], v[112:127]
	v_cvt_pk_bf16_f32 v192, v96, v97
	v_cvt_pk_bf16_f32 v193, v98, v99
	v_cvt_pk_bf16_f32 v194, v100, v101
	v_cvt_pk_bf16_f32 v195, v102, v103
	v_cvt_pk_bf16_f32 v10, v104, v105
	v_cvt_pk_bf16_f32 v11, v106, v107
	v_cvt_pk_bf16_f32 v12, v108, v109
	v_mfma_f32_32x32x16_bf16 v[128:143], v[196:199], v[148:151], v[128:143]
	v_cvt_pk_bf16_f32 v13, v110, v111
	v_cvt_pk_bf16_f32 v6, v80, v81
	v_cvt_pk_bf16_f32 v7, v82, v83
	v_cvt_pk_bf16_f32 v8, v84, v85
	v_cvt_pk_bf16_f32 v9, v86, v87
	v_cvt_pk_bf16_f32 v2, v88, v89
	v_cvt_pk_bf16_f32 v3, v90, v91
	v_mfma_f32_32x32x16_bf16 v[112:127], v[208:211], v[144:147], v[112:127]
	v_cvt_pk_bf16_f32 v4, v92, v93
	v_cvt_pk_bf16_f32 v5, v94, v95
	v_mfma_f32_32x32x16_bf16 v[128:143], v[204:207], v[144:147], v[128:143]
	s_cmp_lt_i32 s80, s72
	s_cbranch_scc1 .Lfm_even
	s_cselect_b64 vcc, -1, 0
	s_nop 8
	v_cndmask_b32_e32 v97, v231, v113, vcc
	v_cndmask_b32_e32 v96, v231, v112, vcc
	v_max_f32_e32 v0, v97, v97
	v_max_f32_e32 v112, v96, v96
	v_cndmask_b32_e32 v99, v231, v115, vcc
	v_cndmask_b32_e32 v98, v231, v114, vcc
	v_max_f32_e32 v0, v112, v0
	v_cndmask_b32_e32 v101, v231, v117, vcc
	v_cndmask_b32_e32 v100, v231, v116, vcc
	v_max3_f32 v0, v0, v98, v99
	v_cndmask_b32_e32 v103, v231, v119, vcc
	v_cndmask_b32_e32 v102, v231, v118, vcc
	v_max3_f32 v0, v0, v100, v101
	v_cndmask_b32_e32 v105, v231, v121, vcc
	v_cndmask_b32_e32 v104, v231, v120, vcc
	v_max3_f32 v0, v0, v102, v103
	v_cndmask_b32_e32 v107, v231, v123, vcc
	v_cndmask_b32_e32 v106, v231, v122, vcc
	v_max3_f32 v0, v0, v104, v105
	v_cndmask_b32_e32 v109, v231, v125, vcc
	v_cndmask_b32_e32 v108, v231, v124, vcc
	v_max3_f32 v0, v0, v106, v107
	v_cndmask_b32_e32 v111, v231, v127, vcc
	v_cndmask_b32_e32 v110, v231, v126, vcc
	v_max3_f32 v0, v0, v108, v109
	v_cndmask_b32_e32 v81, v231, v129, vcc
	v_cndmask_b32_e32 v80, v231, v128, vcc
	v_max3_f32 v0, v0, v110, v111
	v_cndmask_b32_e32 v83, v231, v131, vcc
	v_cndmask_b32_e32 v82, v231, v130, vcc
	v_max3_f32 v0, v0, v80, v81
	v_cndmask_b32_e32 v85, v231, v133, vcc
	v_cndmask_b32_e32 v84, v231, v132, vcc
	v_max3_f32 v0, v0, v82, v83
	v_cndmask_b32_e32 v87, v231, v135, vcc
	v_cndmask_b32_e32 v86, v231, v134, vcc
	v_max3_f32 v0, v0, v84, v85
	v_cndmask_b32_e32 v89, v231, v137, vcc
	v_cndmask_b32_e32 v88, v231, v136, vcc
	v_max3_f32 v0, v0, v86, v87
	v_cndmask_b32_e32 v91, v231, v139, vcc
	v_cndmask_b32_e32 v90, v231, v138, vcc
	v_max3_f32 v0, v0, v88, v89
	v_lshl_add_u32 v243, s79, 14, v235
	ds_read_b64_tr_b16 v[208:209], v243 offset:0
	v_cndmask_b32_e32 v93, v231, v141, vcc
	v_cndmask_b32_e32 v92, v231, v140, vcc
	v_max3_f32 v0, v0, v90, v91
	ds_read_b64_tr_b16 v[210:211], v243 offset:0x800
	v_cndmask_b32_e32 v95, v231, v143, vcc
	v_cndmask_b32_e32 v94, v231, v142, vcc
	v_max3_f32 v0, v0, v92, v93
	ds_read_b64_tr_b16 v[204:205], v243 offset:0x1000
	v_max3_f32 v0, v0, v94, v95
	ds_read_b64_tr_b16 v[206:207], v243 offset:0x1800
	v_mov_b32_e32 v112, v0
	ds_read_b64_tr_b16 v[200:201], v243 offset:0x2000
	s_nop 1
	v_permlane32_swap_b32_e32 v0, v112
	ds_read_b64_tr_b16 v[202:203], v243 offset:0x2800
	v_max_f32_e32 v112, v112, v112
	v_max_f32_e32 v0, v0, v0
	ds_read_b64_tr_b16 v[196:197], v243 offset:0x3000
	v_max_f32_e32 v112, v0, v112
	ds_read_b64_tr_b16 v[198:199], v243 offset:0x3800
	v_sub_f32_e32 v0, v112, v236
	v_cmp_ge_f32_e32 vcc, s29, v0
	s_cmp_eq_u64 vcc, exec
	v_mov_b32_e32 v0, 1.0
	s_cbranch_scc0 .LBB0_884

.Lresc_mla_even:
	v_cmp_gt_f32_e32 vcc, 1.0, v0
	s_cbranch_vccz .LBB0_881
	s_and_saveexec_b64 s[60:61], s[4:5]
	ds_write_b32 v233, v0 offset:128
	s_or_b64 exec, exec, s[60:61]
	s_waitcnt lgkmcnt(0)
	ds_read_b128 v[2:5], v232 offset:224
	ds_read_b128 v[6:9], v232 offset:192
	ds_read_b128 v[10:13], v232 offset:160
	ds_read_b128 v[112:115], v232 offset:128
	s_waitcnt lgkmcnt(0)
	v_pk_mul_f32 v[78:79], v[78:79], v[4:5]
	v_pk_mul_f32 v[74:75], v[74:75], v[8:9]
	v_pk_mul_f32 v[70:71], v[70:71], v[12:13]
	v_pk_mul_f32 v[66:67], v[66:67], v[114:115]
	v_pk_mul_f32 v[76:77], v[76:77], v[2:3]
	v_pk_mul_f32 v[72:73], v[72:73], v[6:7]
	v_pk_mul_f32 v[68:69], v[68:69], v[10:11]
	v_pk_mul_f32 v[64:65], v[64:65], v[112:113]
	v_pk_mul_f32 v[62:63], v[62:63], v[4:5]
	v_pk_mul_f32 v[58:59], v[58:59], v[8:9]
	v_pk_mul_f32 v[54:55], v[54:55], v[12:13]
	v_pk_mul_f32 v[50:51], v[50:51], v[114:115]
	v_pk_mul_f32 v[60:61], v[60:61], v[2:3]
	v_pk_mul_f32 v[56:57], v[56:57], v[6:7]
	v_pk_mul_f32 v[52:53], v[52:53], v[10:11]
	v_pk_mul_f32 v[48:49], v[48:49], v[112:113]
	v_pk_mul_f32 v[46:47], v[46:47], v[4:5]
	v_pk_mul_f32 v[42:43], v[42:43], v[8:9]
	v_pk_mul_f32 v[38:39], v[38:39], v[12:13]
	v_pk_mul_f32 v[34:35], v[34:35], v[114:115]
	v_pk_mul_f32 v[44:45], v[44:45], v[2:3]
	v_pk_mul_f32 v[40:41], v[40:41], v[6:7]
	v_pk_mul_f32 v[36:37], v[36:37], v[10:11]
	v_pk_mul_f32 v[32:33], v[32:33], v[112:113]
	v_pk_mul_f32 v[30:31], v[30:31], v[4:5]
	v_pk_mul_f32 v[26:27], v[26:27], v[8:9]
	v_pk_mul_f32 v[22:23], v[22:23], v[12:13]
	v_pk_mul_f32 v[18:19], v[18:19], v[114:115]
	v_pk_mul_f32 v[28:29], v[28:29], v[2:3]
	v_pk_mul_f32 v[24:25], v[24:25], v[6:7]
	v_pk_mul_f32 v[20:21], v[20:21], v[10:11]
	v_pk_mul_f32 v[16:17], v[16:17], v[112:113]

.Lfm_odd:
	v_lshl_add_u32 v0, s60, 14, v235
	ds_read_b64_tr_b16 v[208:209], v0 offset:0
	ds_read_b64_tr_b16 v[210:211], v0 offset:0x800
	ds_read_b64_tr_b16 v[204:205], v0 offset:0x1000
	ds_read_b64_tr_b16 v[206:207], v0 offset:0x1800
	ds_read_b64_tr_b16 v[200:201], v0 offset:0x2000
	ds_read_b64_tr_b16 v[202:203], v0 offset:0x2800
	ds_read_b64_tr_b16 v[196:197], v0 offset:0x3000
	ds_read_b64_tr_b16 v[198:199], v0 offset:0x3800
	s_nop 1
	v_max3_f32 v245, v112, v113, v114
	v_max3_f32 v246, v128, v129, v130
	v_max3_f32 v245, v245, v115, v116
	v_max3_f32 v246, v246, v131, v132
	v_max3_f32 v245, v245, v117, v118
	v_max3_f32 v246, v246, v133, v134
	v_max3_f32 v245, v245, v119, v120
	v_max3_f32 v246, v246, v135, v136
	v_max3_f32 v245, v245, v121, v122
	v_max3_f32 v246, v246, v137, v138
	v_max3_f32 v245, v245, v123, v124
	v_max3_f32 v246, v246, v139, v140
	v_max3_f32 v245, v245, v125, v126
	v_max3_f32 v246, v246, v141, v142
	v_max_f32_e32 v245, v245, v127
	v_max_f32_e32 v246, v246, v143
	v_max_f32_e32 v245, v245, v246
	v_mov_b32_e32 v246, v245
	s_nop 1
	v_permlane32_swap_b32_e32 v245, v246
	v_max_f32_e32 v245, v245, v246
	v_sub_f32_e32 v246, v245, v236
	v_cmp_ge_f32_e32 vcc, s29, v246
	s_cmp_eq_u64 vcc, exec
	v_mov_b32_e32 v240, 1.0
	s_cbranch_scc0 .Lfm_odd_ev
.Lfm_odd_exp:
	v_sub_f32_e32 v96, v112, v236
	v_sub_f32_e32 v80, v128, v236
	v_exp_f32_e32 v96, v96
	v_exp_f32_e32 v80, v80
	v_sub_f32_e32 v97, v113, v236
	v_sub_f32_e32 v81, v129, v236
	v_exp_f32_e32 v97, v97
	v_exp_f32_e32 v81, v81
	v_sub_f32_e32 v98, v114, v236
	v_sub_f32_e32 v82, v130, v236
	v_exp_f32_e32 v98, v98
	v_exp_f32_e32 v82, v82
	v_sub_f32_e32 v99, v115, v236
	v_sub_f32_e32 v83, v131, v236
	v_exp_f32_e32 v99, v99
	v_exp_f32_e32 v83, v83
	v_sub_f32_e32 v100, v116, v236
	v_sub_f32_e32 v84, v132, v236
	v_exp_f32_e32 v100, v100
	v_exp_f32_e32 v84, v84
	v_sub_f32_e32 v101, v117, v236
	v_sub_f32_e32 v85, v133, v236
	v_exp_f32_e32 v101, v101
	v_exp_f32_e32 v85, v85
	v_sub_f32_e32 v102, v118, v236
	v_sub_f32_e32 v86, v134, v236
	v_exp_f32_e32 v102, v102
	v_exp_f32_e32 v86, v86
	v_sub_f32_e32 v103, v119, v236
	v_sub_f32_e32 v87, v135, v236
	v_exp_f32_e32 v103, v103
	v_exp_f32_e32 v87, v87
	v_sub_f32_e32 v104, v120, v236
	v_sub_f32_e32 v88, v136, v236
	v_exp_f32_e32 v104, v104
	v_exp_f32_e32 v88, v88
	v_sub_f32_e32 v105, v121, v236
	v_sub_f32_e32 v89, v137, v236
	v_exp_f32_e32 v105, v105
	v_exp_f32_e32 v89, v89
	v_sub_f32_e32 v106, v122, v236
	v_sub_f32_e32 v90, v138, v236
	v_exp_f32_e32 v106, v106
	v_exp_f32_e32 v90, v90
	v_sub_f32_e32 v107, v123, v236
	v_sub_f32_e32 v91, v139, v236
	v_exp_f32_e32 v107, v107
	v_exp_f32_e32 v91, v91
	v_sub_f32_e32 v108, v124, v236
	v_sub_f32_e32 v92, v140, v236
	v_exp_f32_e32 v108, v108
	v_exp_f32_e32 v92, v92
	v_sub_f32_e32 v109, v125, v236
	v_sub_f32_e32 v93, v141, v236
	v_exp_f32_e32 v109, v109
	v_exp_f32_e32 v93, v93
	v_sub_f32_e32 v110, v126, v236
	v_sub_f32_e32 v94, v142, v236
	v_exp_f32_e32 v110, v110
	v_exp_f32_e32 v94, v94
	v_sub_f32_e32 v111, v127, v236
	v_sub_f32_e32 v95, v143, v236
	v_exp_f32_e32 v111, v111
	v_exp_f32_e32 v95, v95
	ds_read_b64_tr_b16 v[112:113], v0 offset:0x200
	ds_read_b64_tr_b16 v[114:115], v0 offset:0xa00
	ds_read_b64_tr_b16 v[116:117], v0 offset:0x1200
	ds_read_b64_tr_b16 v[118:119], v0 offset:0x1a00
	ds_read_b64_tr_b16 v[120:121], v0 offset:0x2200
	ds_read_b64_tr_b16 v[122:123], v0 offset:0x2a00
	ds_read_b64_tr_b16 v[124:125], v0 offset:0x3200
	ds_read_b64_tr_b16 v[126:127], v0 offset:0x3a00
	s_waitcnt lgkmcnt(8)
	v_mfma_f32_32x32x16_bf16 v[64:79], v[192:195], v[208:211], v[64:79]
	v_mfma_f32_32x32x16_bf16 v[64:79], v[10:13], v[204:207], v[64:79]
	v_mfma_f32_32x32x16_bf16 v[64:79], v[6:9], v[200:203], v[64:79]
	v_mfma_f32_32x32x16_bf16 v[64:79], v[2:5], v[196:199], v[64:79]
	ds_read_b64_tr_b16 v[128:129], v0 offset:0x400
	ds_read_b64_tr_b16 v[130:131], v0 offset:0xc00
	ds_read_b64_tr_b16 v[132:133], v0 offset:0x1400
	ds_read_b64_tr_b16 v[134:135], v0 offset:0x1c00
	ds_read_b64_tr_b16 v[136:137], v0 offset:0x2400
	ds_read_b64_tr_b16 v[138:139], v0 offset:0x2c00
	ds_read_b64_tr_b16 v[140:141], v0 offset:0x3400
	ds_read_b64_tr_b16 v[142:143], v0 offset:0x3c00
	s_waitcnt lgkmcnt(8)
	v_mfma_f32_32x32x16_bf16 v[48:63], v[192:195], v[112:115], v[48:63]
	v_mfma_f32_32x32x16_bf16 v[48:63], v[10:13], v[116:119], v[48:63]
	v_mfma_f32_32x32x16_bf16 v[48:63], v[6:9], v[120:123], v[48:63]
	v_mfma_f32_32x32x16_bf16 v[48:63], v[2:5], v[124:127], v[48:63]
	ds_read_b64_tr_b16 v[112:113], v0 offset:0x600
	ds_read_b64_tr_b16 v[114:115], v0 offset:0xe00
	ds_read_b64_tr_b16 v[116:117], v0 offset:0x1600
	ds_read_b64_tr_b16 v[118:119], v0 offset:0x1e00
	ds_read_b64_tr_b16 v[120:121], v0 offset:0x2600
	ds_read_b64_tr_b16 v[122:123], v0 offset:0x2e00
	ds_read_b64_tr_b16 v[124:125], v0 offset:0x3600
	ds_read_b64_tr_b16 v[126:127], v0 offset:0x3e00
	s_waitcnt lgkmcnt(8)
	v_mfma_f32_32x32x16_bf16 v[32:47], v[192:195], v[128:131], v[32:47]
	v_mfma_f32_32x32x16_bf16 v[32:47], v[10:13], v[132:135], v[32:47]
	v_mfma_f32_32x32x16_bf16 v[32:47], v[6:9], v[136:139], v[32:47]
	v_mfma_f32_32x32x16_bf16 v[32:47], v[2:5], v[140:143], v[32:47]
	s_waitcnt lgkmcnt(0)
	v_mfma_f32_32x32x16_bf16 v[16:31], v[192:195], v[112:115], v[16:31]
	v_mfma_f32_32x32x16_bf16 v[16:31], v[10:13], v[116:119], v[16:31]
	v_mfma_f32_32x32x16_bf16 v[16:31], v[6:9], v[120:123], v[16:31]
	v_mfma_f32_32x32x16_bf16 v[16:31], v[2:5], v[124:127], v[16:31]
	s_branch .Lresc_mla_odd
.Lfm_odd_ev:
	v_max_f32_e32 v245, v236, v245
	v_sub_f32_e32 v246, v236, v245
	v_exp_f32_e32 v240, v246
	v_mov_b32_e32 v236, v245
	s_branch .Lfm_odd_exp
.Lfm_even:
	v_lshl_add_u32 v243, s79, 14, v235
	ds_read_b64_tr_b16 v[208:209], v243 offset:0
	ds_read_b64_tr_b16 v[210:211], v243 offset:0x800
	ds_read_b64_tr_b16 v[204:205], v243 offset:0x1000
	ds_read_b64_tr_b16 v[206:207], v243 offset:0x1800
	ds_read_b64_tr_b16 v[200:201], v243 offset:0x2000
	ds_read_b64_tr_b16 v[202:203], v243 offset:0x2800
	ds_read_b64_tr_b16 v[196:197], v243 offset:0x3000
	ds_read_b64_tr_b16 v[198:199], v243 offset:0x3800
	s_nop 1
	v_max3_f32 v245, v112, v113, v114
	v_max3_f32 v246, v128, v129, v130
	v_max3_f32 v245, v245, v115, v116
	v_max3_f32 v246, v246, v131, v132
	v_max3_f32 v245, v245, v117, v118
	v_max3_f32 v246, v246, v133, v134
	v_max3_f32 v245, v245, v119, v120
	v_max3_f32 v246, v246, v135, v136
	v_max3_f32 v245, v245, v121, v122
	v_max3_f32 v246, v246, v137, v138
	v_max3_f32 v245, v245, v123, v124
	v_max3_f32 v246, v246, v139, v140
	v_max3_f32 v245, v245, v125, v126
	v_max3_f32 v246, v246, v141, v142
	v_max_f32_e32 v245, v245, v127
	v_max_f32_e32 v246, v246, v143
	v_max_f32_e32 v245, v245, v246
	v_mov_b32_e32 v246, v245
	s_nop 1
	v_permlane32_swap_b32_e32 v245, v246
	v_max_f32_e32 v245, v245, v246
	v_sub_f32_e32 v246, v245, v236
	v_cmp_ge_f32_e32 vcc, s29, v246
	s_cmp_eq_u64 vcc, exec
	v_mov_b32_e32 v0, 1.0
	s_cbranch_scc0 .Lfm_even_ev
.Lfm_even_exp:
	v_sub_f32_e32 v96, v112, v236
	v_sub_f32_e32 v80, v128, v236
	v_exp_f32_e32 v96, v96
	v_exp_f32_e32 v80, v80
	v_sub_f32_e32 v97, v113, v236
	v_sub_f32_e32 v81, v129, v236
	v_exp_f32_e32 v97, v97
	v_exp_f32_e32 v81, v81
	v_sub_f32_e32 v98, v114, v236
	v_sub_f32_e32 v82, v130, v236
	v_exp_f32_e32 v98, v98
	v_exp_f32_e32 v82, v82
	v_sub_f32_e32 v99, v115, v236
	v_sub_f32_e32 v83, v131, v236
	v_exp_f32_e32 v99, v99
	v_exp_f32_e32 v83, v83
	v_sub_f32_e32 v100, v116, v236
	v_sub_f32_e32 v84, v132, v236
	v_exp_f32_e32 v100, v100
	v_exp_f32_e32 v84, v84
	v_sub_f32_e32 v101, v117, v236
	v_sub_f32_e32 v85, v133, v236
	v_exp_f32_e32 v101, v101
	v_exp_f32_e32 v85, v85
	v_sub_f32_e32 v102, v118, v236
	v_sub_f32_e32 v86, v134, v236
	v_exp_f32_e32 v102, v102
	v_exp_f32_e32 v86, v86
	v_sub_f32_e32 v103, v119, v236
	v_sub_f32_e32 v87, v135, v236
	v_exp_f32_e32 v103, v103
	v_exp_f32_e32 v87, v87
	v_sub_f32_e32 v104, v120, v236
	v_sub_f32_e32 v88, v136, v236
	v_exp_f32_e32 v104, v104
	v_exp_f32_e32 v88, v88
	v_sub_f32_e32 v105, v121, v236
	v_sub_f32_e32 v89, v137, v236
	v_exp_f32_e32 v105, v105
	v_exp_f32_e32 v89, v89
	v_sub_f32_e32 v106, v122, v236
	v_sub_f32_e32 v90, v138, v236
	v_exp_f32_e32 v106, v106
	v_exp_f32_e32 v90, v90
	v_sub_f32_e32 v107, v123, v236
	v_sub_f32_e32 v91, v139, v236
	v_exp_f32_e32 v107, v107
	v_exp_f32_e32 v91, v91
	v_sub_f32_e32 v108, v124, v236
	v_sub_f32_e32 v92, v140, v236
	v_exp_f32_e32 v108, v108
	v_exp_f32_e32 v92, v92
	v_sub_f32_e32 v109, v125, v236
	v_sub_f32_e32 v93, v141, v236
	v_exp_f32_e32 v109, v109
	v_exp_f32_e32 v93, v93
	v_sub_f32_e32 v110, v126, v236
	v_sub_f32_e32 v94, v142, v236
	v_exp_f32_e32 v110, v110
	v_exp_f32_e32 v94, v94
	v_sub_f32_e32 v111, v127, v236
	v_sub_f32_e32 v95, v143, v236
	v_exp_f32_e32 v111, v111
	v_exp_f32_e32 v95, v95
	ds_read_b64_tr_b16 v[112:113], v243 offset:0x200
	ds_read_b64_tr_b16 v[114:115], v243 offset:0xa00
	ds_read_b64_tr_b16 v[116:117], v243 offset:0x1200
	ds_read_b64_tr_b16 v[118:119], v243 offset:0x1a00
	ds_read_b64_tr_b16 v[120:121], v243 offset:0x2200
	ds_read_b64_tr_b16 v[122:123], v243 offset:0x2a00
	ds_read_b64_tr_b16 v[124:125], v243 offset:0x3200
	ds_read_b64_tr_b16 v[126:127], v243 offset:0x3a00
	s_waitcnt lgkmcnt(8)
	v_mfma_f32_32x32x16_bf16 v[64:79], v[192:195], v[208:211], v[64:79]
	v_mfma_f32_32x32x16_bf16 v[64:79], v[10:13], v[204:207], v[64:79]
	v_mfma_f32_32x32x16_bf16 v[64:79], v[6:9], v[200:203], v[64:79]
	v_mfma_f32_32x32x16_bf16 v[64:79], v[2:5], v[196:199], v[64:79]
	ds_read_b64_tr_b16 v[128:129], v243 offset:0x400
	ds_read_b64_tr_b16 v[130:131], v243 offset:0xc00
	ds_read_b64_tr_b16 v[132:133], v243 offset:0x1400
	ds_read_b64_tr_b16 v[134:135], v243 offset:0x1c00
	ds_read_b64_tr_b16 v[136:137], v243 offset:0x2400
	ds_read_b64_tr_b16 v[138:139], v243 offset:0x2c00
	ds_read_b64_tr_b16 v[140:141], v243 offset:0x3400
	ds_read_b64_tr_b16 v[142:143], v243 offset:0x3c00
	s_waitcnt lgkmcnt(8)
	v_mfma_f32_32x32x16_bf16 v[48:63], v[192:195], v[112:115], v[48:63]
	v_mfma_f32_32x32x16_bf16 v[48:63], v[10:13], v[116:119], v[48:63]
	v_mfma_f32_32x32x16_bf16 v[48:63], v[6:9], v[120:123], v[48:63]
	v_mfma_f32_32x32x16_bf16 v[48:63], v[2:5], v[124:127], v[48:63]
	ds_read_b64_tr_b16 v[112:113], v243 offset:0x600
	ds_read_b64_tr_b16 v[114:115], v243 offset:0xe00
	ds_read_b64_tr_b16 v[116:117], v243 offset:0x1600
	ds_read_b64_tr_b16 v[118:119], v243 offset:0x1e00
	ds_read_b64_tr_b16 v[120:121], v243 offset:0x2600
	ds_read_b64_tr_b16 v[122:123], v243 offset:0x2e00
	ds_read_b64_tr_b16 v[124:125], v243 offset:0x3600
	ds_read_b64_tr_b16 v[126:127], v243 offset:0x3e00
	s_waitcnt lgkmcnt(8)
	v_mfma_f32_32x32x16_bf16 v[32:47], v[192:195], v[128:131], v[32:47]
	v_mfma_f32_32x32x16_bf16 v[32:47], v[10:13], v[132:135], v[32:47]
	v_mfma_f32_32x32x16_bf16 v[32:47], v[6:9], v[136:139], v[32:47]
	v_mfma_f32_32x32x16_bf16 v[32:47], v[2:5], v[140:143], v[32:47]
	s_waitcnt lgkmcnt(0)
	v_mfma_f32_32x32x16_bf16 v[16:31], v[192:195], v[112:115], v[16:31]
	v_mfma_f32_32x32x16_bf16 v[16:31], v[10:13], v[116:119], v[16:31]
	v_mfma_f32_32x32x16_bf16 v[16:31], v[6:9], v[120:123], v[16:31]
	v_mfma_f32_32x32x16_bf16 v[16:31], v[2:5], v[124:127], v[16:31]
	s_branch .Lresc_mla_even
.Lfm_even_ev:
	v_max_f32_e32 v245, v236, v245
	v_sub_f32_e32 v246, v236, v245
	v_exp_f32_e32 v0, v246
	v_mov_b32_e32 v236, v245
	s_branch .Lfm_even_exp
